# hyena filter-odd + combine loops: sincospif only in trip 0, later trips rotate the kept twiddles by pi/8
# speedup vs baseline: 1.0256x; 1.0005x over previous
.Lhyo_lean:
	s_waitcnt vmcnt(0)
	s_mov_b32 s9, 0x7f800000
	v_sub_f32_e32 v77, v66, v77
	v_sub_f32_e32 v83, v67, v72
	v_sub_f32_e32 v87, v68, v71
	v_sub_f32_e32 v85, v69, v70
	v_mul_f32_e32 v82, 0x3f6c835e, v150
	v_mul_f32_e32 v84, 0x3f6c835e, v151
	v_mul_f32_e32 v86, 0x3f6c835e, v152
	v_mul_f32_e32 v88, 0x3f6c835e, v153
	v_mul_f32_e32 v89, 0x3f6c835e, v154
	v_mul_f32_e32 v90, 0x3f6c835e, v155
	v_mul_f32_e32 v91, 0x3f6c835e, v156
	v_mul_f32_e32 v92, 0x3f6c835e, v157
	v_fmamk_f32 v84, v150, 0x3ec3ef15, v84
	v_fmamk_f32 v150, v151, 0xbec3ef15, v82
	v_mov_b32_e32 v151, v84
	v_fmamk_f32 v88, v152, 0x3ec3ef15, v88
	v_fmamk_f32 v152, v153, 0xbec3ef15, v86
	v_mov_b32_e32 v153, v88
	v_fmamk_f32 v90, v154, 0x3ec3ef15, v90
	v_fmamk_f32 v154, v155, 0xbec3ef15, v89
	v_mov_b32_e32 v155, v90
	v_fmamk_f32 v92, v156, 0x3ec3ef15, v92
	v_fmamk_f32 v156, v157, 0xbec3ef15, v91
	v_mov_b32_e32 v157, v92
	v_mul_f32_e32 v66, v150, v77
	v_mul_f32_e64 v67, v151, -v77
	v_mul_f32_e32 v68, v152, v83
	v_mul_f32_e64 v69, v153, -v83
	v_mul_f32_e32 v88, v154, v87
	v_mul_f32_e64 v89, v155, -v87
	v_mul_f32_e32 v90, v156, v85
	v_mul_f32_e64 v91, v157, -v85
	ds_write_b128 v73, v[66:69]
	ds_write_b128 v73, v[88:91] offset:16
	s_movk_i32 s0, 0xe000
	s_mov_b32 s1, -1
	v_lshl_add_u64 v[78:79], v[78:79], 0, s[0:1]
	s_mov_b64 s[0:1], 0x2000
	v_lshl_add_u64 v[80:81], v[80:81], 0, s[0:1]
	s_movk_i32 s0, 0x37ff
	v_add_u32_e32 v82, 0x800, v76
	v_cmp_lt_i32_e32 vcc, s0, v76
	v_add_u32_e32 v0, 0xfffff800, v0
	v_add_u32_e32 v73, 0x4000, v73
	s_or_b64 s[24:25], vcc, s[24:25]
	v_mov_b32_e32 v76, v82
	s_andn2_b64 exec, exec, s[24:25]
	s_cbranch_execz .LBB0_1057
	s_branch .LBB0_1055
.LBB0_1054:
	s_or_b64 exec, exec, s[0:1]
	v_readfirstlane_b32 s0, v76
	s_cmpk_ge_u32 s0, 0x800
	s_cbranch_scc1 .Lhyo_lean
	s_waitcnt vmcnt(0)
	v_sub_f32_e32 v77, v66, v77
	v_add_u32_e32 v66, 1, v76
	v_sub_f32_e32 v83, v67, v72
	v_cvt_f32_i32_e32 v67, v66
	v_cvt_f32_i32_e32 v66, v76
	v_sub_f32_e32 v85, v69, v70
	v_sub_f32_e32 v87, v68, v71
	s_mov_b32 s9, 0x7f800000
	v_pk_mul_f32 v[66:67], v[66:67], s[28:29] op_sel_hi:[1,0]
	v_xor_b32_e32 v82, 0x80000000, v77
	v_mul_f32_e64 v70, |v66|, 0.5
	v_fract_f32_e32 v71, v70
	v_add_f32_e32 v71, v71, v71
	v_cmp_neq_f32_e32 vcc, s9, v70
	v_cmp_gt_f32_e64 s[0:1], |v66|, 1.0
	v_and_b32_e32 v69, 0x7fffffff, v66
	v_cndmask_b32_e32 v70, 0, v71, vcc
	v_cndmask_b32_e64 v70, |v66|, v70, s[0:1]
	v_add_f32_e32 v71, v70, v70
	v_rndne_f32_e32 v71, v71
	v_fmac_f32_e32 v70, -0.5, v71
	v_mul_f32_e32 v88, v70, v70
	v_fmamk_f32 v89, v88, 0x3e75aa41, v197
	v_fmaak_f32 v89, v88, v89, 0x40234736
	v_fmaak_f32 v89, v88, v89, 0xc0a55e0e
	v_mul_f32_e32 v90, v70, v88
	v_mul_f32_e32 v89, v90, v89
	v_fmac_f32_e32 v89, 0x40490fdb, v70
	v_fmamk_f32 v70, v88, 0x3d4be544, v198
	v_fmaak_f32 v70, v88, v70, 0xbfaad1da
	v_fmaak_f32 v70, v88, v70, 0x4081e0d3
	v_fmaak_f32 v70, v88, v70, 0xc09de9e6
	v_cvt_i32_f32_e32 v71, v71
	v_fma_f32 v70, v88, v70, 1.0
	v_mul_f32_e64 v88, |v67|, 0.5
	v_fract_f32_e32 v90, v88
	v_add_f32_e32 v90, v90, v90
	v_cmp_neq_f32_e32 vcc, s9, v88
	v_cmp_gt_f32_e64 s[0:1], |v67|, 1.0
	v_and_b32_e32 v92, 1, v71
	v_cndmask_b32_e32 v88, 0, v90, vcc
	v_cndmask_b32_e64 v88, |v67|, v88, s[0:1]
	v_cmp_eq_u32_e32 vcc, 0, v92
	v_add_f32_e32 v90, v88, v88
	v_lshlrev_b32_e32 v71, 30, v71
	v_cndmask_b32_e32 v92, v70, v89, vcc
	v_xor_b32_e32 v89, 0x80000000, v89
	v_rndne_f32_e32 v90, v90
	v_cndmask_b32_e32 v70, v89, v70, vcc
	v_and_b32_e32 v71, 0x80000000, v71
	v_xor_b32_e32 v70, v70, v71
	v_cmp_class_f32_e32 vcc, v66, v199
	v_fmac_f32_e32 v88, -0.5, v90
	v_xor_b32_e32 v69, v69, v66
	v_cndmask_b32_e32 v66, v218, v70, vcc
	v_mov_b32_e32 v150, v66
	v_mul_f32_e32 v70, v88, v88
	v_mul_f32_e32 v66, v66, v77
	v_fmamk_f32 v77, v70, 0x3e75aa41, v197
	v_fmaak_f32 v77, v70, v77, 0x40234736
	v_cvt_i32_f32_e32 v91, v90
	v_fmaak_f32 v77, v70, v77, 0xc0a55e0e
	v_mul_f32_e32 v90, v88, v70
	v_mul_f32_e32 v77, v90, v77
	v_fmac_f32_e32 v77, 0x40490fdb, v88
	v_fmamk_f32 v88, v70, 0x3d4be544, v198
	v_fmaak_f32 v88, v70, v88, 0xbfaad1da
	v_fmaak_f32 v88, v70, v88, 0x4081e0d3
	v_fmaak_f32 v88, v70, v88, 0xc09de9e6
	v_fma_f32 v70, v70, v88, 1.0
	v_and_b32_e32 v88, 1, v91
	v_and_b32_e32 v68, 0x7fffffff, v67
	v_cmp_eq_u32_e64 s[0:1], 0, v88
	v_lshlrev_b32_e32 v89, 30, v91
	v_xor_b32_e32 v68, v68, v67
	v_cndmask_b32_e64 v88, v70, v77, s[0:1]
	v_and_b32_e32 v89, 0x80000000, v89
	v_xor_b32_e32 v68, v68, v88
	v_xor_b32_e32 v88, v68, v89
	v_xor_b32_e32 v68, 0x80000000, v77
	v_xor_b32_e32 v69, v69, v92
	v_cndmask_b32_e64 v68, v68, v70, s[0:1]
	v_xor_b32_e32 v68, v68, v89
	v_xor_b32_e32 v70, v69, v71
	v_cmp_class_f32_e64 s[0:1], v67, v199
	v_or_b32_e32 v72, 3, v76
	v_or_b32_e32 v86, 2, v76
	v_cndmask_b32_e64 v69, v218, v68, s[0:1]
	v_cndmask_b32_e32 v68, v218, v70, vcc
	v_cndmask_b32_e64 v67, v218, v88, s[0:1]
	v_mov_b32_e32 v151, v68
	v_mov_b32_e32 v152, v69
	v_mov_b32_e32 v153, v67
	v_pk_mul_f32 v[70:71], v[68:69], v[82:83]
	v_mul_f32_e64 v69, v67, -v83
	v_cvt_f32_i32_e32 v83, v72
	v_cvt_f32_i32_e32 v82, v86
	v_mov_b32_e32 v67, v70
	v_mov_b32_e32 v68, v71
	ds_write_b128 v73, v[66:69]
	v_pk_mul_f32 v[66:67], v[82:83], s[28:29] op_sel_hi:[1,0]
	v_xor_b32_e32 v84, 0x80000000, v87
	v_mul_f32_e64 v70, |v66|, 0.5
	v_fract_f32_e32 v71, v70
	v_add_f32_e32 v71, v71, v71
	v_cmp_neq_f32_e32 vcc, s9, v70
	v_cmp_gt_f32_e64 s[0:1], |v66|, 1.0
	v_and_b32_e32 v69, 0x7fffffff, v66
	v_cndmask_b32_e32 v70, 0, v71, vcc
	v_cndmask_b32_e64 v70, |v66|, v70, s[0:1]
	v_add_f32_e32 v71, v70, v70
	v_rndne_f32_e32 v71, v71
	v_fmac_f32_e32 v70, -0.5, v71
	v_mul_f32_e32 v72, v70, v70
	v_fmamk_f32 v77, v72, 0x3e75aa41, v197
	v_fmaak_f32 v77, v72, v77, 0x40234736
	v_fmaak_f32 v77, v72, v77, 0xc0a55e0e
	v_mul_f32_e32 v82, v70, v72
	v_mul_f32_e32 v77, v82, v77
	v_fmac_f32_e32 v77, 0x40490fdb, v70
	v_fmamk_f32 v70, v72, 0x3d4be544, v198
	v_fmaak_f32 v70, v72, v70, 0xbfaad1da
	v_fmaak_f32 v70, v72, v70, 0x4081e0d3
	v_fmaak_f32 v70, v72, v70, 0xc09de9e6
	v_cvt_i32_f32_e32 v71, v71
	v_fma_f32 v70, v72, v70, 1.0
	v_mul_f32_e64 v72, |v67|, 0.5
	v_fract_f32_e32 v82, v72
	v_add_f32_e32 v82, v82, v82
	v_cmp_neq_f32_e32 vcc, s9, v72
	v_cmp_gt_f32_e64 s[0:1], |v67|, 1.0
	v_and_b32_e32 v86, 1, v71
	v_cndmask_b32_e32 v72, 0, v82, vcc
	v_cndmask_b32_e64 v72, |v67|, v72, s[0:1]
	v_cmp_eq_u32_e32 vcc, 0, v86
	v_add_f32_e32 v82, v72, v72
	v_lshlrev_b32_e32 v71, 30, v71
	v_cndmask_b32_e32 v86, v70, v77, vcc
	v_xor_b32_e32 v77, 0x80000000, v77
	v_rndne_f32_e32 v82, v82
	v_cndmask_b32_e32 v70, v77, v70, vcc
	v_and_b32_e32 v71, 0x80000000, v71
	v_xor_b32_e32 v70, v70, v71
	v_cmp_class_f32_e32 vcc, v66, v199
	v_fmac_f32_e32 v72, -0.5, v82
	v_xor_b32_e32 v69, v69, v66
	v_cndmask_b32_e32 v66, v218, v70, vcc
	v_mov_b32_e32 v154, v66
	v_mul_f32_e32 v70, v72, v72
	v_cvt_i32_f32_e32 v83, v82
	v_fmamk_f32 v82, v70, 0x3e75aa41, v197
	v_fmaak_f32 v82, v70, v82, 0x40234736
	v_xor_b32_e32 v69, v69, v86
	v_fmaak_f32 v82, v70, v82, 0xc0a55e0e
	v_mul_f32_e32 v86, v72, v70
	v_mul_f32_e32 v82, v86, v82
	v_fmac_f32_e32 v82, 0x40490fdb, v72
	v_fmamk_f32 v72, v70, 0x3d4be544, v198
	v_fmaak_f32 v72, v70, v72, 0xbfaad1da
	v_fmaak_f32 v72, v70, v72, 0x4081e0d3
	v_fmaak_f32 v72, v70, v72, 0xc09de9e6
	v_fma_f32 v70, v70, v72, 1.0
	v_and_b32_e32 v72, 1, v83
	v_and_b32_e32 v68, 0x7fffffff, v67
	v_cmp_eq_u32_e64 s[0:1], 0, v72
	v_lshlrev_b32_e32 v77, 30, v83
	v_xor_b32_e32 v68, v68, v67
	v_cndmask_b32_e64 v72, v70, v82, s[0:1]
	v_and_b32_e32 v77, 0x80000000, v77
	v_xor_b32_e32 v68, v68, v72
	v_xor_b32_e32 v72, v68, v77
	v_xor_b32_e32 v68, 0x80000000, v82
	v_cndmask_b32_e64 v68, v68, v70, s[0:1]
	v_xor_b32_e32 v68, v68, v77
	v_cmp_class_f32_e64 s[0:1], v67, v199
	v_xor_b32_e32 v70, v69, v71
	v_mul_f32_e32 v66, v87, v66
	v_cndmask_b32_e64 v69, v218, v68, s[0:1]
	v_cndmask_b32_e64 v67, v218, v72, s[0:1]
	s_movk_i32 s0, 0xe000
	v_cndmask_b32_e32 v68, v218, v70, vcc
	v_mov_b32_e32 v155, v68
	v_mov_b32_e32 v156, v69
	v_mov_b32_e32 v157, v67
	s_mov_b32 s1, -1
	v_pk_mul_f32 v[70:71], v[68:69], v[84:85]
	v_lshl_add_u64 v[78:79], v[78:79], 0, s[0:1]
	s_mov_b64 s[0:1], 0x2000
	v_mul_f32_e64 v69, v67, -v85
	v_mov_b32_e32 v67, v70
	v_mov_b32_e32 v68, v71
	v_lshl_add_u64 v[80:81], v[80:81], 0, s[0:1]
	s_movk_i32 s0, 0x37ff
	ds_write_b128 v73, v[66:69] offset:16
	v_add_u32_e32 v66, 0x800, v76
	v_cmp_lt_i32_e32 vcc, s0, v76
	v_add_u32_e32 v0, 0xfffff800, v0
	v_add_u32_e32 v73, 0x4000, v73
	s_or_b64 s[24:25], vcc, s[24:25]
	v_mov_b32_e32 v76, v66
	s_andn2_b64 exec, exec, s[24:25]
	s_cbranch_execz .LBB0_1057

.LBB0_1086:
	s_or_b64 exec, exec, s[0:1]
	s_waitcnt vmcnt(1)
	v_and_b32_e32 v53, 0xffff0000, v40
	v_lshlrev_b32_e32 v40, 16, v40
	v_fma_f32 v46, v48, v51, v49
	v_fma_f32 v54, v48, v40, v49
	v_and_b32_e32 v47, 0xffff0000, v41
	v_lshlrev_b32_e32 v41, 16, v41
	v_fmac_f32_e32 v46, v26, v40
	v_fmac_f32_e32 v54, v26, v53
	v_fma_f32 v56, v48, v53, v49
	v_fmac_f32_e32 v46, v27, v53
	v_fmac_f32_e32 v54, v27, v41
	v_fmac_f32_e32 v56, v26, v41
	v_fma_f32 v40, v48, v41, v49
	v_fma_f32 v41, v48, v52, v49
	s_waitcnt vmcnt(0)
	v_and_b32_e32 v53, 0xffff0000, v44
	v_lshlrev_b32_e32 v52, 16, v44
	v_pk_mul_f32 v[58:59], v[26:27], v[52:53]
	v_lshlrev_b32_e32 v44, 16, v45
	v_add_f32_e32 v41, v58, v41
	v_fmac_f32_e32 v56, v27, v47
	v_fmac_f32_e32 v40, v26, v47
	v_add_f32_e32 v47, v59, v41
	v_fma_f32 v41, v48, v52, v49
	v_mov_b32_e32 v52, v44
	v_fmac_f32_e32 v40, v27, v42
	v_fma_f32 v42, v48, v53, v49
	v_pk_mul_f32 v[52:53], v[30:31], v[52:53]
	v_and_b32_e32 v45, 0xffff0000, v45
	v_add_f32_e32 v41, v53, v41
	v_add_f32_e32 v55, v52, v41
	v_pk_mul_f32 v[52:53], v[26:27], v[44:45]
	s_mov_b32 s30, 0x38800000
	v_add_f32_e32 v41, v52, v42
	v_add_f32_e32 v57, v53, v41
	v_fma_f32 v41, v48, v44, v49
	v_add_u32_e32 v44, 1, v0
	v_mov_b32_e32 v42, v45
	v_cvt_f32_i32_e32 v44, v44
	v_cvt_f32_i32_e32 v45, v0
	v_pk_mul_f32 v[42:43], v[26:27], v[42:43]
	s_mov_b32 s4, 0x7f800000
	v_add_f32_e32 v41, v42, v41
	v_add_f32_e32 v41, v41, v43
	v_readfirstlane_b32 s0, v0
	s_cmpk_ge_u32 s0, 0x800
	s_cbranch_scc1 .Lhyc_lean
	v_pk_mul_f32 v[42:43], v[44:45], s[30:31] op_sel_hi:[1,0]
	s_movk_i32 s9, 0x1f8
	v_and_b32_e32 v45, 0x7fffffff, v43
	v_and_b32_e32 v44, 0x7fffffff, v42
	v_pk_mul_f32 v[52:53], v[44:45], 0.5 op_sel_hi:[1,0]
	v_cmp_gt_f32_e64 s[0:1], |v43|, 1.0
	v_fract_f32_e32 v51, v53
	v_add_f32_e32 v51, v51, v51
	v_cmp_neq_f32_e32 vcc, s4, v53
	v_xor_b32_e32 v45, v45, v43
	s_brev_b32 s5, 1
	v_cndmask_b32_e32 v51, 0, v51, vcc
	v_cndmask_b32_e64 v51, |v43|, v51, s[0:1]
	v_add_f32_e32 v53, v51, v51
	v_rndne_f32_e32 v53, v53
	v_fmac_f32_e32 v51, -0.5, v53
	v_mul_f32_e32 v58, v51, v51
	v_fmamk_f32 v59, v58, 0x3e75aa41, v197
	v_fmaak_f32 v59, v58, v59, 0x40234736
	v_fmaak_f32 v59, v58, v59, 0xc0a55e0e
	v_mul_f32_e32 v60, v51, v58
	v_mul_f32_e32 v59, v60, v59
	v_cvt_i32_f32_e32 v53, v53
	v_fmac_f32_e32 v59, 0x40490fdb, v51
	v_fmamk_f32 v51, v58, 0x3d4be544, v198
	v_fmaak_f32 v51, v58, v51, 0xbfaad1da
	v_fmaak_f32 v51, v58, v51, 0x4081e0d3
	v_fmaak_f32 v51, v58, v51, 0xc09de9e6
	v_fma_f32 v51, v58, v51, 1.0
	v_lshlrev_b32_e32 v58, 30, v53
	v_and_b32_e32 v53, 1, v53
	v_cmp_eq_u32_e32 vcc, 0, v53
	v_and_b32_e32 v60, 0x80000000, v58
	s_brev_b32 s38, 28
	v_cndmask_b32_e32 v53, v51, v59, vcc
	v_xor_b32_e32 v45, v45, v53
	v_xor_b32_e32 v53, 0x80000000, v59
	v_xor_b32_e32 v45, v45, v60
	v_cndmask_b32_e32 v51, v53, v51, vcc
	v_cmp_class_f32_e64 vcc, v43, s9
	v_bitop3_b32 v51, v51, v58, s5 bitop3:0x78
	v_cmp_gt_f32_e64 s[0:1], |v42|, 1.0
	v_cndmask_b32_e32 v60, v218, v45, vcc
	v_cndmask_b32_e32 v58, v218, v51, vcc
	v_mov_b32_e32 v150, v58
	v_mov_b32_e32 v151, v60
	s_waitcnt lgkmcnt(1)
	v_pk_mul_f32 v[60:61], v[22:23], v[60:61] op_sel:[1,0] op_sel_hi:[0,0]
	v_pk_fma_f32 v[62:63], v[22:23], v[58:59], v[60:61] neg_lo:[0,0,1] neg_hi:[0,0,1]
	v_pk_fma_f32 v[22:23], v[22:23], v[58:59], v[60:61] op_sel_hi:[1,0,1]
	v_cmp_neq_f32_e32 vcc, s4, v52
	v_mov_b32_e32 v63, v23
	v_pk_add_f32 v[18:19], v[18:19], v[62:63]
	v_xor_b32_e32 v44, v44, v42
	v_pk_mul_f32 v[18:19], v[18:19], s[38:39] op_sel_hi:[1,0]
	s_nop 0
	v_pk_fma_f32 v[14:15], v[28:29], v[14:15], v[18:19]
	v_fract_f32_e32 v18, v52
	v_add_f32_e32 v18, v18, v18
	v_cndmask_b32_e32 v18, 0, v18, vcc
	v_cndmask_b32_e64 v18, |v42|, v18, s[0:1]
	v_add_f32_e32 v19, v18, v18
	v_rndne_f32_e32 v19, v19
	v_fmac_f32_e32 v18, -0.5, v19
	v_mul_f32_e32 v22, v18, v18
	v_fmamk_f32 v23, v22, 0x3e75aa41, v197
	v_fmaak_f32 v23, v22, v23, 0x40234736
	v_fmaak_f32 v23, v22, v23, 0xc0a55e0e
	v_mul_f32_e32 v43, v18, v22
	v_mul_f32_e32 v23, v43, v23
	v_cvt_i32_f32_e32 v19, v19
	v_fmac_f32_e32 v23, 0x40490fdb, v18
	v_fmamk_f32 v18, v22, 0x3d4be544, v198
	v_fmaak_f32 v18, v22, v18, 0xbfaad1da
	v_fmaak_f32 v18, v22, v18, 0x4081e0d3
	v_fmaak_f32 v18, v22, v18, 0xc09de9e6
	v_fma_f32 v18, v22, v18, 1.0
	v_lshlrev_b32_e32 v22, 30, v19
	v_and_b32_e32 v19, 1, v19
	v_cmp_eq_u32_e32 vcc, 0, v19
	v_and_b32_e32 v43, 0x80000000, v22
	v_pk_mul_f32 v[14:15], v[14:15], v[46:47]
	v_cndmask_b32_e32 v19, v18, v23, vcc
	v_xor_b32_e32 v19, v44, v19
	v_xor_b32_e32 v23, 0x80000000, v23
	v_xor_b32_e32 v19, v19, v43
	v_cndmask_b32_e32 v18, v23, v18, vcc
	v_cmp_class_f32_e64 vcc, v42, s9
	v_bitop3_b32 v18, v18, v22, s5 bitop3:0x78
	s_nop 0
	v_cndmask_b32_e32 v22, v218, v19, vcc
	v_cndmask_b32_e32 v18, v218, v18, vcc
	v_mov_b32_e32 v152, v18
	v_mov_b32_e32 v153, v22
	v_pk_mul_f32 v[22:23], v[24:25], v[22:23] op_sel:[1,0] op_sel_hi:[0,0]
	v_pk_fma_f32 v[42:43], v[24:25], v[18:19], v[22:23] neg_lo:[0,0,1] neg_hi:[0,0,1]
	v_pk_fma_f32 v[18:19], v[24:25], v[18:19], v[22:23] op_sel_hi:[1,0,1]
	v_or_b32_e32 v22, 3, v0
	v_mov_b32_e32 v43, v19
	v_pk_add_f32 v[18:19], v[20:21], v[42:43]
	v_or_b32_e32 v20, 2, v0
	v_cvt_f32_i32_e32 v21, v20
	v_cvt_f32_i32_e32 v20, v22
	v_pk_mul_f32 v[18:19], v[18:19], s[38:39] op_sel_hi:[1,0]
	s_nop 0
	v_pk_fma_f32 v[16:17], v[28:29], v[16:17], v[18:19]
	v_pk_mul_f32 v[18:19], v[20:21], s[30:31] op_sel_hi:[1,0]
	v_pk_mul_f32 v[16:17], v[16:17], v[54:55]
	v_and_b32_e32 v21, 0x7fffffff, v19
	v_and_b32_e32 v20, 0x7fffffff, v18
	v_pk_mul_f32 v[22:23], v[20:21], 0.5 op_sel_hi:[1,0]
	v_cmp_gt_f32_e64 s[0:1], |v19|, 1.0
	v_fract_f32_e32 v24, v23
	v_add_f32_e32 v24, v24, v24
	v_cmp_neq_f32_e32 vcc, s4, v23
	v_xor_b32_e32 v21, v21, v19
	v_xor_b32_e32 v20, v20, v18
	v_cndmask_b32_e32 v23, 0, v24, vcc
	v_cndmask_b32_e64 v23, |v19|, v23, s[0:1]
	v_add_f32_e32 v24, v23, v23
	v_rndne_f32_e32 v24, v24
	v_fmac_f32_e32 v23, -0.5, v24
	v_mul_f32_e32 v25, v23, v23
	v_fmamk_f32 v42, v25, 0x3e75aa41, v197
	v_fmaak_f32 v42, v25, v42, 0x40234736
	v_fmaak_f32 v42, v25, v42, 0xc0a55e0e
	v_mul_f32_e32 v43, v23, v25
	v_mul_f32_e32 v42, v43, v42
	v_cvt_i32_f32_e32 v24, v24
	v_fmac_f32_e32 v42, 0x40490fdb, v23
	v_fmamk_f32 v23, v25, 0x3d4be544, v198
	v_fmaak_f32 v23, v25, v23, 0xbfaad1da
	v_fmaak_f32 v23, v25, v23, 0x4081e0d3
	v_fmaak_f32 v23, v25, v23, 0xc09de9e6
	v_fma_f32 v23, v25, v23, 1.0
	v_lshlrev_b32_e32 v25, 30, v24
	v_and_b32_e32 v24, 1, v24
	v_cmp_eq_u32_e32 vcc, 0, v24
	v_and_b32_e32 v43, 0x80000000, v25
	v_cmp_gt_f32_e64 s[0:1], |v18|, 1.0
	v_cndmask_b32_e32 v24, v23, v42, vcc
	v_xor_b32_e32 v21, v21, v24
	v_xor_b32_e32 v24, 0x80000000, v42
	v_xor_b32_e32 v21, v21, v43
	v_cndmask_b32_e32 v23, v24, v23, vcc
	v_cmp_class_f32_e64 vcc, v19, s9
	v_bitop3_b32 v23, v23, v25, s5 bitop3:0x78
	s_nop 0
	v_cndmask_b32_e32 v42, v218, v21, vcc
	v_cndmask_b32_e32 v24, v218, v23, vcc
	v_mov_b32_e32 v154, v24
	v_mov_b32_e32 v155, v42
	s_waitcnt lgkmcnt(0)
	v_pk_mul_f32 v[42:43], v[10:11], v[42:43] op_sel:[1,0] op_sel_hi:[0,0]
	v_pk_fma_f32 v[44:45], v[10:11], v[24:25], v[42:43] neg_lo:[0,0,1] neg_hi:[0,0,1]
	v_pk_fma_f32 v[10:11], v[10:11], v[24:25], v[42:43] op_sel_hi:[1,0,1]
	v_cmp_neq_f32_e32 vcc, s4, v22
	v_mov_b32_e32 v45, v11
	v_pk_add_f32 v[6:7], v[6:7], v[44:45]
	s_nop 0
	v_pk_mul_f32 v[6:7], v[6:7], s[38:39] op_sel_hi:[1,0]
	s_nop 0
	v_pk_fma_f32 v[2:3], v[28:29], v[2:3], v[6:7]
	v_fract_f32_e32 v6, v22
	v_add_f32_e32 v6, v6, v6
	v_cndmask_b32_e32 v6, 0, v6, vcc
	v_cndmask_b32_e64 v6, |v18|, v6, s[0:1]
	v_add_f32_e32 v7, v6, v6
	v_rndne_f32_e32 v7, v7
	v_fmac_f32_e32 v6, -0.5, v7
	v_mul_f32_e32 v10, v6, v6
	v_fmamk_f32 v11, v10, 0x3e75aa41, v197
	v_fmaak_f32 v11, v10, v11, 0x40234736
	v_fmaak_f32 v11, v10, v11, 0xc0a55e0e
	v_mul_f32_e32 v19, v6, v10
	v_mul_f32_e32 v11, v19, v11
	v_cvt_i32_f32_e32 v7, v7
	v_fmac_f32_e32 v11, 0x40490fdb, v6
	v_fmamk_f32 v6, v10, 0x3d4be544, v198
	v_fmaak_f32 v6, v10, v6, 0xbfaad1da
	v_fmaak_f32 v6, v10, v6, 0x4081e0d3
	v_fmaak_f32 v6, v10, v6, 0xc09de9e6
	v_fma_f32 v6, v10, v6, 1.0
	v_lshlrev_b32_e32 v10, 30, v7
	v_and_b32_e32 v7, 1, v7
	v_cmp_eq_u32_e32 vcc, 0, v7
	v_and_b32_e32 v19, 0x80000000, v10
	v_pk_mul_f32 v[2:3], v[2:3], v[56:57]
	v_cndmask_b32_e32 v7, v6, v11, vcc
	v_xor_b32_e32 v7, v20, v7
	v_xor_b32_e32 v11, 0x80000000, v11
	v_xor_b32_e32 v7, v7, v19
	v_cndmask_b32_e32 v6, v11, v6, vcc
	v_cmp_class_f32_e64 vcc, v18, s9
	v_bitop3_b32 v6, v6, v10, s5 bitop3:0x78
	s_mov_b64 s[0:1], -1
	v_cndmask_b32_e32 v10, v218, v7, vcc
	v_cndmask_b32_e32 v6, v218, v6, vcc
	v_mov_b32_e32 v156, v6
	v_mov_b32_e32 v157, v10
	v_pk_mul_f32 v[10:11], v[12:13], v[10:11] op_sel:[1,0] op_sel_hi:[0,0]
	v_pk_fma_f32 v[18:19], v[12:13], v[6:7], v[10:11] neg_lo:[0,0,1] neg_hi:[0,0,1]
	v_pk_fma_f32 v[6:7], v[12:13], v[6:7], v[10:11] op_sel_hi:[1,0,1]
	s_and_b64 vcc, exec, s[22:23]
	v_mov_b32_e32 v19, v7
	v_pk_add_f32 v[6:7], v[8:9], v[18:19]
	s_nop 0
	v_pk_mul_f32 v[6:7], v[6:7], s[38:39] op_sel_hi:[1,0]
	s_nop 0
	v_pk_fma_f32 v[4:5], v[28:29], v[4:5], v[6:7]
	s_nop 0
	v_pk_mul_f32 v[4:5], v[4:5], v[40:41]
.Lhyc_tail:
	s_cbranch_vccz .LBB0_1088
	ds_write_b128 v50, v[14:17]
	ds_write_b128 v50, v[2:5] offset:16
	s_mov_b64 s[0:1], 0

.Lhyc_lean:
	s_movk_i32 s9, 0x1f8
	s_brev_b32 s5, 1
	s_brev_b32 s38, 28
	v_mul_f32_e32 v42, 0x3f6c835e, v150
	v_mul_f32_e32 v43, 0x3f6c835e, v151
	v_mul_f32_e32 v44, 0x3f6c835e, v152
	v_mul_f32_e32 v45, 0x3f6c835e, v153
	v_mul_f32_e32 v51, 0x3f6c835e, v154
	v_mul_f32_e32 v52, 0x3f6c835e, v155
	v_mul_f32_e32 v53, 0x3f6c835e, v156
	v_mul_f32_e32 v59, 0x3f6c835e, v157
	v_fmamk_f32 v43, v150, 0x3ec3ef15, v43
	v_fmamk_f32 v150, v151, 0xbec3ef15, v42
	v_mov_b32_e32 v151, v43
	v_fmamk_f32 v45, v152, 0x3ec3ef15, v45
	v_fmamk_f32 v152, v153, 0xbec3ef15, v44
	v_mov_b32_e32 v153, v45
	v_fmamk_f32 v52, v154, 0x3ec3ef15, v52
	v_fmamk_f32 v154, v155, 0xbec3ef15, v51
	v_mov_b32_e32 v155, v52
	v_fmamk_f32 v59, v156, 0x3ec3ef15, v59
	v_fmamk_f32 v156, v157, 0xbec3ef15, v53
	v_mov_b32_e32 v157, v59
	v_mov_b32_e32 v58, v150
	v_mov_b32_e32 v60, v151
	s_nop 0
	s_waitcnt lgkmcnt(1)
	v_pk_mul_f32 v[60:61], v[22:23], v[60:61] op_sel:[1,0] op_sel_hi:[0,0]
	v_pk_fma_f32 v[62:63], v[22:23], v[58:59], v[60:61] neg_lo:[0,0,1] neg_hi:[0,0,1]
	v_pk_fma_f32 v[22:23], v[22:23], v[58:59], v[60:61] op_sel_hi:[1,0,1]
	v_mov_b32_e32 v63, v23
	v_pk_add_f32 v[18:19], v[18:19], v[62:63]
	s_nop 0
	v_pk_mul_f32 v[18:19], v[18:19], s[38:39] op_sel_hi:[1,0]
	s_nop 0
	v_pk_fma_f32 v[14:15], v[28:29], v[14:15], v[18:19]
	v_pk_mul_f32 v[14:15], v[14:15], v[46:47]
	v_mov_b32_e32 v18, v152
	v_mov_b32_e32 v22, v153
	s_nop 0
	v_pk_mul_f32 v[22:23], v[24:25], v[22:23] op_sel:[1,0] op_sel_hi:[0,0]
	v_pk_fma_f32 v[42:43], v[24:25], v[18:19], v[22:23] neg_lo:[0,0,1] neg_hi:[0,0,1]
	v_pk_fma_f32 v[18:19], v[24:25], v[18:19], v[22:23] op_sel_hi:[1,0,1]
	v_mov_b32_e32 v43, v19
	v_pk_add_f32 v[18:19], v[20:21], v[42:43]
	s_nop 0
	v_pk_mul_f32 v[18:19], v[18:19], s[38:39] op_sel_hi:[1,0]
	s_nop 0
	v_pk_fma_f32 v[16:17], v[28:29], v[16:17], v[18:19]
	v_pk_mul_f32 v[16:17], v[16:17], v[54:55]
	v_mov_b32_e32 v24, v154
	v_mov_b32_e32 v42, v155
	s_nop 0
	s_waitcnt lgkmcnt(0)
	v_pk_mul_f32 v[42:43], v[10:11], v[42:43] op_sel:[1,0] op_sel_hi:[0,0]
	v_pk_fma_f32 v[44:45], v[10:11], v[24:25], v[42:43] neg_lo:[0,0,1] neg_hi:[0,0,1]
	v_pk_fma_f32 v[10:11], v[10:11], v[24:25], v[42:43] op_sel_hi:[1,0,1]
	v_mov_b32_e32 v45, v11
	v_pk_add_f32 v[6:7], v[6:7], v[44:45]
	s_nop 0
	v_pk_mul_f32 v[6:7], v[6:7], s[38:39] op_sel_hi:[1,0]
	s_nop 0
	v_pk_fma_f32 v[2:3], v[28:29], v[2:3], v[6:7]
	v_pk_mul_f32 v[2:3], v[2:3], v[56:57]
	v_mov_b32_e32 v6, v156
	v_mov_b32_e32 v10, v157
	s_nop 0
	v_pk_mul_f32 v[10:11], v[12:13], v[10:11] op_sel:[1,0] op_sel_hi:[0,0]
	v_pk_fma_f32 v[18:19], v[12:13], v[6:7], v[10:11] neg_lo:[0,0,1] neg_hi:[0,0,1]
	v_pk_fma_f32 v[6:7], v[12:13], v[6:7], v[10:11] op_sel_hi:[1,0,1]
	v_mov_b32_e32 v19, v7
	v_pk_add_f32 v[6:7], v[8:9], v[18:19]
	s_nop 0
	v_pk_mul_f32 v[6:7], v[6:7], s[38:39] op_sel_hi:[1,0]
	s_nop 0
	v_pk_fma_f32 v[4:5], v[28:29], v[4:5], v[6:7]
	v_pk_mul_f32 v[4:5], v[4:5], v[40:41]
	s_mov_b64 s[0:1], -1
	s_and_b64 vcc, exec, s[22:23]
	s_branch .Lhyc_tail
